# P10 conv fix-up: loop-invariant workspace pointer loaded once instead of five waited kernarg s_loads per trip
# baseline (speedup 1.0000x reference)
; #define INP(k) ((const float*)(GAS const float*)KARG64(8 * (k)))
;     __device__ __forceinline__ void init(int G_, int c) { G = G_; sp.init(MAINR, 1024, G_, c); sg.init(MAINR, 512, G_, c); }
;     __device__ __forceinline__ bool next(int i, pg8::Unit& u) const { const int L = i * G + c; if (L >= NG * 8) return false; u.pm = (L >> 3) * 9 + (L & 7); u.pn = L >> 3; return true; }
; #define AM ((float*)(WSP() + WS_AM))
; #define AT ((float*)(WSP() + WS_AT))
; __global__ void __launch_bounds__(NWAVES * 64, 2) hybrid_fwd(Params P) {
;     ...
;     if (IN(10)) {
;         pg8::StaticOrder S; S.init(MAINR, 1024, G, bx);
;         {
;             const float* cw = INP(26); pg8::Unit uu; int lastpm = -1;
;             for (int ui = 0; S.next(ui, uu); ++ui) {
;                 const int pm = uu.pm; if (pm == lastpm) continue; lastpm = pm;
;                 for (int i = tid; i < 2 * (DFF / 4); i += 512) {
;                     const int q = i % (DFF / 4), row = i / (DFF / 4), pr = pm * 2 + row, hid = 4 * q;
;                     const float* a2p = (pm & 15) == 0 ? AM + hid : AT + (size_t)((pm - 1) * 2) * DFF + hid;
;                     const f32x4 am2 = *(const f32x4*)a2p, am1 = *(const f32x4*)(a2p + DFF);
;                     const f32x4 w0 = *(const f32x4*)(cw + hid), w1 = *(const f32x4*)(cw + DFF + hid);
.LBB0_1289:
	s_cmp_lt_i32 s78, 11
	s_cselect_b64 s[6:7], -1, 0
	s_and_b64 s[4:5], s[6:7], s[4:5]
	s_andn2_b64 vcc, exec, s[4:5]
	s_cbranch_vccnz .LBB0_1336
	s_load_dwordx2 s[98:99], s[0:1], 0xf0
	s_mov_b64 s[4:5], s[0:1]
	s_load_dwordx2 s[6:7], s[4:5], 0xd0
	s_ashr_i32 s26, s3, 31
	s_ashr_i32 s27, s2, 31
	s_waitcnt vmcnt(0)
	v_lshlrev_b32_e32 v6, 2, v218
	s_mov_b32 s12, -1
	s_waitcnt lgkmcnt(0)
	s_add_u32 s8, s6, 0x2c00
	s_addc_u32 s9, s7, 0
	s_mov_b32 s16, 0
	v_mov_b64_e32 v[0:1], 0x200
	v_mov_b64_e32 v[2:3], 0x1ff
	s_movk_i32 s17, 0x2c00
	s_movk_i32 s18, 0x2c0
	s_movk_i32 s19, 0x2bf
	v_mov_b32_e32 v5, 0
	s_mov_b32 s20, 0x2800000
	s_mov_b32 s21, 0x2b00000
	s_mov_b32 s22, 0xc0135761
	s_movk_i32 s23, 0x1600
	s_movk_i32 s24, 0x37f
	s_branch .LBB0_1294

; __device__ __forceinline__ unsigned cvtpk(float lo, float hi) { f32x2 v = {lo, hi}; bf16x2_t b = __builtin_convertvector(v, bf16x2_t); return __builtin_bit_cast(unsigned, b); }
; __device__ __forceinline__ f32x4 gelu4(f32x4 v) { return (f32x4){fgelu(v[0]), fgelu(v[1]), fgelu(v[2]), fgelu(v[3])}; }
; #define AM ((float*)(WSP() + WS_AM))
; #define CP ((float*)(WSP() + WS_CP))
; #define BP ((float*)(WSP() + WS_BP))
; #define AT ((float*)(WSP() + WS_AT))
; __global__ void __launch_bounds__(NWAVES * 64, 2) hybrid_fwd(Params P) {
;     ...
;                 for (int i = tid; i < 2 * (DFF / 4); i += 512) {
;                     const int q = i % (DFF / 4), row = i / (DFF / 4), pr = pm * 2 + row, hid = 4 * q;
;                     const float* a2p = (pm & 15) == 0 ? AM + hid : AT + (size_t)((pm - 1) * 2) * DFF + hid;
;                     const f32x4 am2 = *(const f32x4*)a2p, am1 = *(const f32x4*)(a2p + DFF);
;                     const f32x4 w0 = *(const f32x4*)(cw + hid), w1 = *(const f32x4*)(cw + DFF + hid);
;                     f32x4 c = *(const f32x4*)(CP + (size_t)pr * DFF + hid); const f32x4 bg = *(const f32x4*)(BP + (size_t)pr * DFF + hid);
;                     if (row == 0) c += w1 * am1 + w0 * am2; else c += w0 * am1;
;                     const f32x4 o = gelu4(c) * bg;
;                     u32x2 w; w.x = cvtpk(o[0], o[1]); w.y = cvtpk(o[2], o[3]);
;                     *(u32x2*)(ACT + (size_t)(pm * 256 + row) * DFF + hid) = w;
.LBB0_1303:
	v_add_u32_e32 v4, 0xfffff500, v7
	v_cmp_gt_u32_e64 s[4:5], s18, v8
	s_nop 1
	v_cndmask_b32_e64 v4, v4, v7, s[4:5]
	v_lshlrev_b64 v[30:31], 2, v[4:5]
	v_lshl_add_u64 v[18:19], s[14:15], 0, v[30:31]
	v_add_co_u32_e32 v20, vcc, 0x2000, v18
	v_lshl_add_u64 v[22:23], s[8:9], 0, v[30:31]
	s_nop 0
	v_addc_co_u32_e32 v21, vcc, 0, v19, vcc
	global_load_dwordx4 v[10:13], v[18:19], off
	global_load_dwordx4 v[14:17], v[20:21], off offset:3072
	v_lshl_add_u64 v[18:19], s[6:7], 0, v[30:31]
	s_mov_b64 s[14:15], s[0:1]
	global_load_dwordx4 v[18:21], v[18:19], off
	v_cmp_lt_u32_e32 vcc, s19, v8
	global_load_dwordx4 v[22:25], v[22:23], off
	s_mov_b64 s[14:15], s[98:99]
	v_cndmask_b32_e64 v9, 0, 1, vcc
	v_or_b32_e32 v34, s28, v9
	v_or_b32_e32 v35, s31, v9
	v_add_u32_e32 v7, 0x800, v7
	s_waitcnt lgkmcnt(0)
	v_mov_b64_e32 v[26:27], s[14:15]
	v_mad_i64_i32 v[26:27], s[14:15], v34, s17, v[26:27]
	v_lshl_add_u64 v[26:27], v[26:27], 0, v[30:31]
	v_add_co_u32_e32 v26, vcc, s20, v26
	s_mov_b64 s[14:15], s[0:1]
	s_nop 0
	v_addc_co_u32_e32 v27, vcc, 0, v27, vcc
	global_load_dwordx4 v[26:29], v[26:27], off
	s_mov_b64 s[14:15], s[98:99]
	s_waitcnt lgkmcnt(0)
	v_mov_b64_e32 v[32:33], s[14:15]
	v_mad_i64_i32 v[32:33], s[14:15], v34, s17, v[32:33]
	v_lshl_add_u64 v[30:31], v[32:33], 0, v[30:31]
	v_add_co_u32_e32 v30, vcc, s21, v30
	s_mov_b64 s[14:15], s[0:1]
	s_nop 0
	v_addc_co_u32_e32 v31, vcc, 0, v31, vcc
	global_load_dwordx4 v[30:33], v[30:31], off
	s_mov_b64 s[14:15], s[98:99]
	v_add_u32_e32 v34, 0x200, v8
	v_cmp_lt_u32_e32 vcc, s24, v8
	s_or_b64 s[12:13], vcc, s[12:13]
	s_waitcnt lgkmcnt(0)
	v_mov_b64_e32 v[8:9], s[14:15]
	v_mad_i64_i32 v[8:9], s[14:15], v35, s23, v[8:9]
	v_lshl_add_u64 v[8:9], v[4:5], 1, v[8:9]
	v_add_co_u32_e32 v8, vcc, 0xca00000, v8
	s_waitcnt vmcnt(2)
	v_pk_mul_f32 v[24:25], v[16:17], v[24:25]
	v_pk_mul_f32 v[22:23], v[14:15], v[22:23]
	v_pk_mul_f32 v[16:17], v[16:17], v[20:21]
	v_pk_mul_f32 v[14:15], v[14:15], v[18:19]
	v_pk_fma_f32 v[12:13], v[12:13], v[20:21], v[24:25]
	v_pk_fma_f32 v[10:11], v[10:11], v[18:19], v[22:23]
	v_cndmask_b32_e64 v13, v17, v13, s[4:5]
	v_cndmask_b32_e64 v12, v16, v12, s[4:5]
	v_cndmask_b32_e64 v11, v15, v11, s[4:5]
	v_cndmask_b32_e64 v10, v14, v10, s[4:5]
	v_addc_co_u32_e32 v9, vcc, 0, v9, vcc
	s_waitcnt vmcnt(1)
	v_pk_add_f32 v[12:13], v[28:29], v[12:13]
	v_pk_add_f32 v[10:11], v[26:27], v[10:11]
	v_mul_f32_e32 v15, 0x3dd2d3e8, v12
	v_mul_f32_e32 v4, 0x3dd2d3e8, v10
	v_mul_f32_e32 v14, 0x3dd2d3e8, v11
	v_mul_f32_e32 v16, 0x3dd2d3e8, v13
	v_fma_f32 v4, -v10, v4, s22
	v_fma_f32 v14, -v11, v14, s22
	v_fma_f32 v15, -v12, v15, s22
	v_fma_f32 v16, -v13, v16, s22
	v_mul_f32_e32 v4, v10, v4
	v_mul_f32_e32 v14, v11, v14
	v_mul_f32_e32 v15, v12, v15
	v_mul_f32_e32 v16, v13, v16
	v_exp_f32_e32 v4, v4
	v_exp_f32_e32 v14, v14
	v_exp_f32_e32 v15, v15
	v_exp_f32_e32 v16, v16
	v_add_f32_e32 v4, 1.0, v4
	v_add_f32_e32 v17, 1.0, v14
	v_add_f32_e32 v18, 1.0, v15
	v_add_f32_e32 v19, 1.0, v16
	v_rcp_f32_e32 v14, v4
	v_rcp_f32_e32 v15, v17
	v_rcp_f32_e32 v16, v18
	v_rcp_f32_e32 v17, v19
	v_pk_mul_f32 v[10:11], v[10:11], v[14:15]
	s_waitcnt vmcnt(0)
	v_pk_mul_f32 v[10:11], v[30:31], v[10:11]
	v_pk_mul_f32 v[12:13], v[12:13], v[16:17]
	v_cvt_pk_bf16_f32 v10, v10, v11
	v_pk_mul_f32 v[12:13], v[32:33], v[12:13]
	s_nop 0
	v_cvt_pk_bf16_f32 v11, v12, v13
	global_store_dwordx2 v[8:9], v[10:11], off
	v_mov_b32_e32 v8, v34
	s_andn2_b64 exec, exec, s[12:13]
	s_cbranch_execz .LBB0_1291
.LBB0_1304:
	s_and_b64 vcc, exec, s[10:11]
	s_cbranch_vccz .LBB0_1306
	s_mov_b64 s[4:5], s[0:1]
	s_mov_b64 s[4:5], s[98:99]
	s_waitcnt lgkmcnt(0)
	s_add_u32 s4, s4, s30
	s_addc_u32 s5, s5, s29
	s_add_u32 s14, s4, 0x2e00000
	s_addc_u32 s15, s5, 0
	s_cbranch_execnz .LBB0_1303
	s_branch .LBB0_1307
.LBB0_1306:
.LBB0_1307:
	s_mov_b64 s[4:5], s[0:1]
	s_mov_b64 s[4:5], s[98:99]
	s_waitcnt lgkmcnt(0)
	s_add_u32 s14, s4, 0x59000
	s_addc_u32 s15, s5, 0
	s_branch .LBB0_1303
